# conversion schedule variant: 1 item per wave in gate_up phase, second item at the next w_in phase start
# baseline (speedup 1.0000x reference)
; __device__ __forceinline__ ArgsP args_ptr() { ArgsP p = (ArgsP)__builtin_amdgcn_kernarg_segment_ptr(); asm volatile("" : "+s"(p)); return p; }
; #define TIDS() int lane_ = (int)__builtin_amdgcn_mbcnt_hi(~0u, __builtin_amdgcn_mbcnt_lo(~0u, 0u)); asm volatile("" : "+v"(lane_)); const int lane = lane_ & 63, wave = wave_s & 7, tid = wave * 64 + lane; const int G = gridDim.x, bx = blockIdx.x; (void)lane; (void)wave; (void)tid; (void)G; (void)bx
; __device__ __forceinline__ void convert_layer(ArgsP a, int L, int first, int stride, int lane) {
;     unsigned char* ws = a->ws;
;     bf16* WIN = (bf16*)(ws + WS_WIN); bf16* WOUT = (bf16*)(ws + WS_WOUT); bf16* WGU = (bf16*)(ws + WS_WGU); bf16* WDN = (bf16*)(ws + WS_WDN);
;     for (int r = first; r < I_L; r += stride) {
;         if (r < I_IN) transpose_item(a->in[3] + (size_t)L * D * INW, D, INW, WIN + (size_t)L * INW * D, a->in[2] + L * D, 1, 0, r, lane);
;         else if (r < I_IN + I_OUT) transpose_item(a->in[4] + (size_t)L * D * D, D, D, WOUT + (size_t)L * D * D, nullptr, 0, 0, r - I_IN, lane);
;         else if (r < I_IN + I_OUT + I_GU) transpose_item(a->in[18] + (size_t)L * D * GU, D, GU, WGU + (size_t)L * GU * D, a->in[17] + L * D, 2, 0, r - I_IN - I_OUT, lane);
;         else transpose_item(a->in[19] + (size_t)L * FFN * D, FFN, D, WDN + (size_t)L * D * FFN, nullptr, 0, 0, r - I_IN - I_OUT - I_GU, lane);
;     }
; }
; __device__ __forceinline__ void phase_A(unsigned char* lds, int wave_s, int L) {
;     ArgsP a = args_ptr(); TIDS(); unsigned char* ws = a->ws; const int j = L >> 1;
;     pg8::Gemm g{(bf16*)(ws + WS_XB), (bf16*)(ws + WS_WIN) + (size_t)L * INW * D, M, INW, D}; pg8::StaticOrder S; S.init(M, INW, G, bx);
;     pg8::EpiU E{(bf16*)(ws + WS_U), (const float*)(ws + WS_SS), L & 1, a->in[10] + j * 64, a->in[11] + j * 64, a->in[7] + L * 64, 0.125f * 1.4426950408889634f};
;     if (L + 1 < DEPTH && bx >= 128 && bx < 224) { convert_layer(args_ptr(), L + 1, (bx - 128) * NWAVES + wave, 96 * NWAVES, lane); asm volatile("s_waitcnt vmcnt(0)" ::: "memory"); }
;     pg8::gemm_phase<pg8::EpiU, pg8::StaticOrder, true, true>((pg8::PG8_LAS_T*)lds, g, S, E, tid);
.LBB0_677:
	s_or_b64 exec, exec, s[10:11]
	s_mov_b64 s[4:5], s[96:97]
	s_waitcnt lgkmcnt(0)
	s_barrier
	s_cmp_lt_u32 s2, 0x80
	s_cbranch_scc1 .Lcx2_skip
	s_cmp_ge_u32 s2, 0x100
	s_cbranch_scc1 .Lcx2_skip
	v_mov_b32_e32 v128, v2
	v_mov_b32_e32 v129, v3
	v_mov_b32_e32 v130, v64
	v_mov_b32_e32 v131, v65
	v_mov_b32_e32 v132, v66
	v_mov_b32_e32 v133, v67
	v_mov_b32_e32 v134, v68
	v_mov_b32_e32 v135, v69
	v_mov_b32_e32 v136, v70
	v_mov_b32_e32 v137, v71
	v_mov_b32_e32 v138, v72
	v_mov_b32_e32 v139, v73
	v_mov_b32_e32 v140, v74
	v_mov_b32_e32 v141, v75
	v_mov_b32_e32 v142, v76
	v_mov_b32_e32 v143, v77
	v_mov_b32_e32 v144, v78
	v_mov_b32_e32 v145, v79
	v_mov_b32_e32 v146, v81
	v_mov_b32_e32 v147, v82
	v_mov_b32_e32 v148, v83
	v_mov_b32_e32 v149, v84
	v_mov_b32_e32 v150, v85
	v_mov_b32_e32 v151, v86
	v_mov_b32_e32 v152, v87
	v_mov_b32_e32 v153, v88
	v_mov_b32_e32 v154, v89
	v_mov_b32_e32 v155, v90
	v_mov_b32_e32 v156, v91
	v_writelane_b32 v253, s4, 0
	v_writelane_b32 v253, s5, 1
	v_writelane_b32 v253, s6, 2
	v_writelane_b32 v253, s7, 3
	v_writelane_b32 v253, s34, 4
	v_writelane_b32 v253, s35, 5
	v_writelane_b32 v253, s36, 6
	v_writelane_b32 v253, s38, 7
	v_writelane_b32 v253, s39, 8
	v_writelane_b32 v253, s42, 9
	v_writelane_b32 v253, s43, 10
	v_writelane_b32 v253, s44, 11
	v_writelane_b32 v253, s46, 12
	v_writelane_b32 v253, s70, 13
	v_writelane_b32 v253, s71, 14
	v_writelane_b32 v253, s72, 15
	v_writelane_b32 v253, s86, 16
	v_writelane_b32 v253, s87, 17
	v_and_b32_e32 v80, 63, v201
	s_mov_b64 s[12:13], s[96:97]
	s_load_dwordx2 s[4:5], s[12:13], 0xa8
	v_readlane_b32 s1, v252, 2
	v_readlane_b32 s14, v252, 1
	s_nop 3
	s_add_i32 s1, s1, s14
	s_add_i32 s1, s1, 0x300
	v_lshlrev_b32_e32 v0, 2, v80
	s_waitcnt lgkmcnt(0)
	s_add_u32 s14, s4, 0x4e80000
	s_addc_u32 s15, s5, 0
	s_add_u32 s16, s4, 0x2800000
	s_addc_u32 s17, s5, 0
	s_add_u32 s18, s4, 0x1700000
	s_addc_u32 s19, s5, 0
	s_add_u32 s22, s4, 0x600000
	s_addc_u32 s23, s5, 0
	s_lshl_b32 s3, s1, 6
	v_and_b32_e32 v81, 0x80, v0
	v_or_b32_e32 v82, s3, v80
	s_lshl_b32 s26, s1, 5
	s_lshl_b32 s27, s1, 2
	v_mov_b32_e32 v13, 0
	s_movk_i32 s30, 0x7fff
	s_mov_b32 s31, 0xffff0000
	v_mov_b32_e32 v83, 0x1000
	v_mov_b32_e32 v84, 1
	s_mov_b32 s33, 0xa0f000
	s_mov_b32 s34, 0xa11000
	s_mov_b32 s35, 0xa14000
	s_mov_b32 s36, 0xa16000
	s_mov_b32 s37, 0xa19000
	s_mov_b32 s38, 0xa1b000
	s_mov_b32 s39, 0xa1e000
	s_mov_b32 s40, 0xa20000
	s_mov_b32 s41, 0xa23000
	s_mov_b32 s42, 0xa25000
	s_mov_b32 s43, 0xa28000
	s_mov_b32 s44, 0xa2a000
	s_mov_b32 s45, 0xa2d000
	s_mov_b32 s46, 0xa2f000
	s_mov_b32 s47, 0xa32000
	s_mov_b32 s48, 0xa34000
	s_mov_b32 s49, 0xa37000
	s_mov_b32 s50, 0xa39000
	s_mov_b32 s51, 0xa3c000
	s_mov_b32 s52, 0xa3e000
	s_mov_b32 s53, 0xa41000
	s_mov_b32 s54, 0xa43000
	s_mov_b32 s55, 0xa46000
	s_mov_b32 s56, 0xa48000
	s_mov_b32 s57, 0xa4b000
	s_mov_b32 s58, 0xa4d000
	s_mov_b32 s59, 0xa50000
	s_mov_b32 s60, 0xa52000
	s_mov_b32 s61, 0xa55000
	s_mov_b32 s62, 0xa57000
	s_mov_b32 s63, 0xa5a000
	s_mov_b32 s64, 0xa5c000
	s_mov_b32 s65, 0xa5f000
	s_mov_b32 s66, 0xa61000
	s_mov_b32 s67, 0xa64000
	s_mov_b32 s68, 0xa66000
	s_mov_b32 s69, 0xa69000
	s_mov_b32 s70, 0xa6b000
	s_mov_b32 s71, 0xa6e000
	s_mov_b32 s72, 0xa70000
	s_mov_b32 s73, 0xa73000
	s_mov_b32 s74, 0xa75000
	s_mov_b32 s75, 0xa78000
	s_mov_b32 s76, 0xa7a000
	s_mov_b32 s77, 0xa7d000
	s_mov_b32 s78, 0xa7f000
	s_mov_b32 s79, 0xa82000
	s_mov_b32 s80, 0xa84000
	s_mov_b32 s81, 0xa87000
	s_mov_b32 s82, 0xa89000
	s_mov_b32 s83, 0xa8c000
	s_mov_b32 s84, 0xa8e000
	s_mov_b32 s85, 0xa91000
	s_mov_b32 s86, 0xa93000
	s_mov_b32 s87, 0xa96000
	s_mov_b32 s88, 0xa98000
	s_mov_b32 s89, 0xa9b000
	s_mov_b32 s90, 0xa9d000
	s_mov_b32 s25, 0
	s_branch .Lcx2_89

; __device__ __forceinline__ ArgsP args_ptr() { ArgsP p = (ArgsP)__builtin_amdgcn_kernarg_segment_ptr(); asm volatile("" : "+s"(p)); return p; }
; __device__ __forceinline__ void convert_layer(ArgsP a, int L, int first, int stride, int lane) {
;     unsigned char* ws = a->ws;
;     bf16* WIN = (bf16*)(ws + WS_WIN); bf16* WOUT = (bf16*)(ws + WS_WOUT); bf16* WGU = (bf16*)(ws + WS_WGU); bf16* WDN = (bf16*)(ws + WS_WDN);
;     for (int r = first; r < I_L; r += stride) {
;         if (r < I_IN) transpose_item(a->in[3] + (size_t)L * D * INW, D, INW, WIN + (size_t)L * INW * D, a->in[2] + L * D, 1, 0, r, lane);
;         else if (r < I_IN + I_OUT) transpose_item(a->in[4] + (size_t)L * D * D, D, D, WOUT + (size_t)L * D * D, nullptr, 0, 0, r - I_IN, lane);
;         else if (r < I_IN + I_OUT + I_GU) transpose_item(a->in[18] + (size_t)L * D * GU, D, GU, WGU + (size_t)L * GU * D, a->in[17] + L * D, 2, 0, r - I_IN - I_OUT, lane);
;         else transpose_item(a->in[19] + (size_t)L * FFN * D, FFN, D, WDN + (size_t)L * D * FFN, nullptr, 0, 0, r - I_IN - I_OUT - I_GU, lane);
;     }
; }
; __device__ __forceinline__ void phase_A(unsigned char* lds, int wave_s, int L) {
;     ...
;     if (L + 1 < DEPTH && bx >= 128 && bx < 224) { convert_layer(args_ptr(), L + 1, (bx - 128) * NWAVES + wave, 96 * NWAVES, lane); asm volatile("s_waitcnt vmcnt(0)" ::: "memory"); }
.Lcx2_skip:
	s_cmp_lt_u32 s2, 0xe0
	s_cbranch_scc1 .Lcx3_skip
	s_cmp_ge_u32 s2, 0xf8
	s_cbranch_scc1 .Lcx3_skip
	v_mov_b32_e32 v128, v2
	v_mov_b32_e32 v129, v3
	v_mov_b32_e32 v130, v64
	v_mov_b32_e32 v131, v65
	v_mov_b32_e32 v132, v66
	v_mov_b32_e32 v133, v67
	v_mov_b32_e32 v134, v68
	v_mov_b32_e32 v135, v69
	v_mov_b32_e32 v136, v70
	v_mov_b32_e32 v137, v71
	v_mov_b32_e32 v138, v72
	v_mov_b32_e32 v139, v73
	v_mov_b32_e32 v140, v74
	v_mov_b32_e32 v141, v75
	v_mov_b32_e32 v142, v76
	v_mov_b32_e32 v143, v77
	v_mov_b32_e32 v144, v78
	v_mov_b32_e32 v145, v79
	v_mov_b32_e32 v146, v81
	v_mov_b32_e32 v147, v82
	v_mov_b32_e32 v148, v83
	v_mov_b32_e32 v149, v84
	v_mov_b32_e32 v150, v85
	v_mov_b32_e32 v151, v86
	v_mov_b32_e32 v152, v87
	v_mov_b32_e32 v153, v88
	v_mov_b32_e32 v154, v89
	v_mov_b32_e32 v155, v90
	v_mov_b32_e32 v156, v91
	v_writelane_b32 v253, s4, 0
	v_writelane_b32 v253, s5, 1
	v_writelane_b32 v253, s6, 2
	v_writelane_b32 v253, s7, 3
	v_writelane_b32 v253, s34, 4
	v_writelane_b32 v253, s35, 5
	v_writelane_b32 v253, s36, 6
	v_writelane_b32 v253, s38, 7
	v_writelane_b32 v253, s39, 8
	v_writelane_b32 v253, s42, 9
	v_writelane_b32 v253, s43, 10
	v_writelane_b32 v253, s44, 11
	v_writelane_b32 v253, s46, 12
	v_writelane_b32 v253, s70, 13
	v_writelane_b32 v253, s71, 14
	v_writelane_b32 v253, s72, 15
	v_writelane_b32 v253, s86, 16
	v_writelane_b32 v253, s87, 17
	v_and_b32_e32 v80, 63, v201
	s_mov_b64 s[12:13], s[96:97]
	s_load_dwordx2 s[4:5], s[12:13], 0xa8
	v_readlane_b32 s1, v252, 2
	v_readlane_b32 s14, v252, 1
	s_nop 3
	s_add_i32 s1, s1, s14
	s_add_i32 s1, s1, 0x400
	v_lshlrev_b32_e32 v0, 2, v80
	s_waitcnt lgkmcnt(0)
	s_add_u32 s14, s4, 0x4e80000
	s_addc_u32 s15, s5, 0
	s_add_u32 s16, s4, 0x2800000
	s_addc_u32 s17, s5, 0
	s_add_u32 s18, s4, 0x1700000
	s_addc_u32 s19, s5, 0
	s_add_u32 s22, s4, 0x600000
	s_addc_u32 s23, s5, 0
	s_lshl_b32 s3, s1, 6
	v_and_b32_e32 v81, 0x80, v0
	v_or_b32_e32 v82, s3, v80
	s_lshl_b32 s26, s1, 5
	s_lshl_b32 s27, s1, 2
	v_mov_b32_e32 v13, 0
	s_movk_i32 s30, 0x7fff
	s_mov_b32 s31, 0xffff0000
	v_mov_b32_e32 v83, 0x1000
	v_mov_b32_e32 v84, 1
	s_mov_b32 s33, 0xa0f000
	s_mov_b32 s34, 0xa11000
	s_mov_b32 s35, 0xa14000
	s_mov_b32 s36, 0xa16000
	s_mov_b32 s37, 0xa19000
	s_mov_b32 s38, 0xa1b000
	s_mov_b32 s39, 0xa1e000
	s_mov_b32 s40, 0xa20000
	s_mov_b32 s41, 0xa23000
	s_mov_b32 s42, 0xa25000
	s_mov_b32 s43, 0xa28000
	s_mov_b32 s44, 0xa2a000
	s_mov_b32 s45, 0xa2d000
	s_mov_b32 s46, 0xa2f000
	s_mov_b32 s47, 0xa32000
	s_mov_b32 s48, 0xa34000
	s_mov_b32 s49, 0xa37000
	s_mov_b32 s50, 0xa39000
	s_mov_b32 s51, 0xa3c000
	s_mov_b32 s52, 0xa3e000
	s_mov_b32 s53, 0xa41000
	s_mov_b32 s54, 0xa43000
	s_mov_b32 s55, 0xa46000
	s_mov_b32 s56, 0xa48000
	s_mov_b32 s57, 0xa4b000
	s_mov_b32 s58, 0xa4d000
	s_mov_b32 s59, 0xa50000
	s_mov_b32 s60, 0xa52000
	s_mov_b32 s61, 0xa55000
	s_mov_b32 s62, 0xa57000
	s_mov_b32 s63, 0xa5a000
	s_mov_b32 s64, 0xa5c000
	s_mov_b32 s65, 0xa5f000
	s_mov_b32 s66, 0xa61000
	s_mov_b32 s67, 0xa64000
	s_mov_b32 s68, 0xa66000
	s_mov_b32 s69, 0xa69000
	s_mov_b32 s70, 0xa6b000
	s_mov_b32 s71, 0xa6e000
	s_mov_b32 s72, 0xa70000
	s_mov_b32 s73, 0xa73000
	s_mov_b32 s74, 0xa75000
	s_mov_b32 s75, 0xa78000
	s_mov_b32 s76, 0xa7a000
	s_mov_b32 s77, 0xa7d000
	s_mov_b32 s78, 0xa7f000
	s_mov_b32 s79, 0xa82000
	s_mov_b32 s80, 0xa84000
	s_mov_b32 s81, 0xa87000
	s_mov_b32 s82, 0xa89000
	s_mov_b32 s83, 0xa8c000
	s_mov_b32 s84, 0xa8e000
	s_mov_b32 s85, 0xa91000
	s_mov_b32 s86, 0xa93000
	s_mov_b32 s87, 0xa96000
	s_mov_b32 s88, 0xa98000
	s_mov_b32 s89, 0xa9b000
	s_mov_b32 s90, 0xa9d000
	s_mov_b32 s25, 0
	s_branch .Lcx3_89

; __device__ __forceinline__ ArgsP args_ptr() { ArgsP p = (ArgsP)__builtin_amdgcn_kernarg_segment_ptr(); asm volatile("" : "+s"(p)); return p; }
; __device__ __forceinline__ void convert_layer(ArgsP a, int L, int first, int stride, int lane) {
;     unsigned char* ws = a->ws;
;     bf16* WIN = (bf16*)(ws + WS_WIN); bf16* WOUT = (bf16*)(ws + WS_WOUT); bf16* WGU = (bf16*)(ws + WS_WGU); bf16* WDN = (bf16*)(ws + WS_WDN);
;     for (int r = first; r < I_L; r += stride) {
;         if (r < I_IN) transpose_item(a->in[3] + (size_t)L * D * INW, D, INW, WIN + (size_t)L * INW * D, a->in[2] + L * D, 1, 0, r, lane);
;         else if (r < I_IN + I_OUT) transpose_item(a->in[4] + (size_t)L * D * D, D, D, WOUT + (size_t)L * D * D, nullptr, 0, 0, r - I_IN, lane);
;         else if (r < I_IN + I_OUT + I_GU) transpose_item(a->in[18] + (size_t)L * D * GU, D, GU, WGU + (size_t)L * GU * D, a->in[17] + L * D, 2, 0, r - I_IN - I_OUT, lane);
;         else transpose_item(a->in[19] + (size_t)L * FFN * D, FFN, D, WDN + (size_t)L * D * FFN, nullptr, 0, 0, r - I_IN - I_OUT - I_GU, lane);
;     }
; }
; __device__ __forceinline__ void phase_A(unsigned char* lds, int wave_s, int L) {
;     ...
;     if (L + 1 < DEPTH && bx >= 128 && bx < 224) { convert_layer(args_ptr(), L + 1, (bx - 128) * NWAVES + wave, 96 * NWAVES, lane); asm volatile("s_waitcnt vmcnt(0)" ::: "memory"); }
.LBB0_1153:
	s_or_b64 exec, exec, s[16:17]
	v_readlane_b32 s12, v252, 15
	v_readlane_b32 s13, v252, 16
	s_waitcnt lgkmcnt(0)
	s_barrier
	s_cmp_lt_u32 s2, 0x80
	s_cbranch_scc1 .Lcx5_skip
	s_cmp_ge_u32 s2, 0x100
	s_cbranch_scc1 .Lcx5_skip
	v_mov_b32_e32 v128, v1
	v_mov_b32_e32 v129, v2
	v_mov_b32_e32 v130, v3
	v_mov_b32_e32 v131, v64
	v_mov_b32_e32 v132, v65
	v_mov_b32_e32 v133, v66
	v_mov_b32_e32 v134, v67
	v_mov_b32_e32 v135, v68
	v_mov_b32_e32 v136, v69
	v_mov_b32_e32 v137, v70
	v_mov_b32_e32 v138, v71
	v_mov_b32_e32 v139, v72
	v_mov_b32_e32 v140, v73
	v_mov_b32_e32 v141, v74
	v_mov_b32_e32 v142, v75
	v_mov_b32_e32 v143, v76
	v_mov_b32_e32 v144, v77
	v_mov_b32_e32 v145, v78
	v_mov_b32_e32 v146, v79
	v_mov_b32_e32 v147, v81
	v_mov_b32_e32 v148, v82
	v_mov_b32_e32 v149, v83
	v_mov_b32_e32 v150, v84
	v_mov_b32_e32 v151, v85
	v_mov_b32_e32 v152, v86
	v_mov_b32_e32 v153, v87
	v_mov_b32_e32 v154, v88
	v_mov_b32_e32 v155, v89
	v_mov_b32_e32 v156, v90
	v_mov_b32_e32 v157, v91
	v_writelane_b32 v253, s1, 0
	v_writelane_b32 v253, s30, 1
	v_writelane_b32 v253, s31, 2
	v_writelane_b32 v253, s34, 3
	v_writelane_b32 v253, s35, 4
	v_writelane_b32 v253, s36, 5
	v_writelane_b32 v253, s37, 6
	v_writelane_b32 v253, s38, 7
	v_writelane_b32 v253, s39, 8
	v_writelane_b32 v253, s41, 9
	v_writelane_b32 v253, s44, 10
	v_writelane_b32 v253, s45, 11
	v_writelane_b32 v253, s46, 12
	v_writelane_b32 v253, s47, 13
	v_writelane_b32 v253, s48, 14
	v_writelane_b32 v253, s49, 15
	v_writelane_b32 v253, s50, 16
	v_writelane_b32 v253, s52, 17
	v_writelane_b32 v253, s63, 18
	v_writelane_b32 v253, s64, 19
	v_writelane_b32 v253, s65, 20
	v_writelane_b32 v253, s74, 21
	v_writelane_b32 v253, s75, 22
	v_writelane_b32 v253, s77, 23
	v_writelane_b32 v253, s82, 24
	v_writelane_b32 v253, s83, 25
	v_writelane_b32 v253, s84, 26
	v_writelane_b32 v253, s85, 27
	v_and_b32_e32 v80, 63, v201
	v_readlane_b32 s24, v252, 15
	v_readlane_b32 s25, v252, 16
	s_nop 3
	s_load_dwordx2 s[4:5], s[24:25], 0xa8
	v_readlane_b32 s1, v252, 2
	v_readlane_b32 s14, v252, 1
	s_nop 3
	s_add_i32 s1, s1, s14
	s_add_i32 s1, s1, 0x300
	v_lshlrev_b32_e32 v0, 2, v80
	s_waitcnt lgkmcnt(0)
	s_add_u32 s26, s4, 0x5400000
	s_addc_u32 s27, s5, 0
	s_add_u32 s34, s4, 0x3300000
	s_addc_u32 s35, s5, 0
	s_add_u32 s36, s4, 0x1900000
	s_addc_u32 s37, s5, 0
	s_add_u32 s38, s4, 0xb00000
	s_addc_u32 s39, s5, 0
	s_lshl_b32 s3, s1, 6
	v_and_b32_e32 v81, 0x80, v0
	v_or_b32_e32 v82, s3, v80
	s_lshl_b32 s4, s1, 5
	s_lshl_b32 s5, s1, 2
	v_mov_b32_e32 v13, 0
	s_movk_i32 s30, 0x7fff
	s_mov_b32 s31, 0xffff0000
	v_mov_b32_e32 v83, 0x2000
	v_mov_b32_e32 v84, 1
	s_mov_b32 s33, 0x1439000
	s_mov_b32 s44, 0x143c000
	s_mov_b32 s45, 0x143e000
	s_mov_b32 s46, 0x1441000
	s_mov_b32 s47, 0x1443000
	s_mov_b32 s48, 0x1446000
	s_mov_b32 s49, 0x1448000
	s_mov_b32 s50, 0x144b000
	s_mov_b32 s51, 0x144d000
	s_mov_b32 s52, 0x1450000
	s_mov_b32 s53, 0x1452000
	s_mov_b32 s54, 0x1455000
	s_mov_b32 s55, 0x1457000
	s_mov_b32 s56, 0x145a000
	s_mov_b32 s57, 0x145c000
	s_mov_b32 s58, 0x145f000
	s_mov_b32 s59, 0x1461000
	s_mov_b32 s60, 0x1464000
	s_mov_b32 s61, 0x1466000
	s_mov_b32 s62, 0x1469000
	s_mov_b32 s63, 0x146b000
	s_mov_b32 s64, 0x146e000
	s_mov_b32 s65, 0x1470000
	s_mov_b32 s66, 0x1473000
	s_mov_b32 s67, 0x1475000
	s_mov_b32 s68, 0x1478000
	s_mov_b32 s69, 0x147a000
	s_mov_b32 s70, 0x147d000
	s_mov_b32 s71, 0x147f000
	s_mov_b32 s72, 0x1482000
	s_mov_b32 s73, 0x1484000
	s_mov_b32 s74, 0x1487000
	s_mov_b32 s75, 0x1489000
	s_mov_b32 s76, 0x148c000
	s_mov_b32 s77, 0x148e000
	s_mov_b32 s78, 0x1491000
	s_mov_b32 s79, 0x1493000
	s_mov_b32 s80, 0x1496000
	s_mov_b32 s81, 0x1498000
	s_mov_b32 s82, 0x149b000
	s_mov_b32 s83, 0x149d000
	s_mov_b32 s41, 0
	s_branch .Lcx5_681

; __device__ __forceinline__ ArgsP args_ptr() { ArgsP p = (ArgsP)__builtin_amdgcn_kernarg_segment_ptr(); asm volatile("" : "+s"(p)); return p; }
; __device__ __forceinline__ void convert_layer(ArgsP a, int L, int first, int stride, int lane) {
;     unsigned char* ws = a->ws;
;     bf16* WIN = (bf16*)(ws + WS_WIN); bf16* WOUT = (bf16*)(ws + WS_WOUT); bf16* WGU = (bf16*)(ws + WS_WGU); bf16* WDN = (bf16*)(ws + WS_WDN);
;     for (int r = first; r < I_L; r += stride) {
;         if (r < I_IN) transpose_item(a->in[3] + (size_t)L * D * INW, D, INW, WIN + (size_t)L * INW * D, a->in[2] + L * D, 1, 0, r, lane);
;         else if (r < I_IN + I_OUT) transpose_item(a->in[4] + (size_t)L * D * D, D, D, WOUT + (size_t)L * D * D, nullptr, 0, 0, r - I_IN, lane);
;         else if (r < I_IN + I_OUT + I_GU) transpose_item(a->in[18] + (size_t)L * D * GU, D, GU, WGU + (size_t)L * GU * D, a->in[17] + L * D, 2, 0, r - I_IN - I_OUT, lane);
;         else transpose_item(a->in[19] + (size_t)L * FFN * D, FFN, D, WDN + (size_t)L * D * FFN, nullptr, 0, 0, r - I_IN - I_OUT - I_GU, lane);
;     }
; }
; __device__ __forceinline__ void phase_A(unsigned char* lds, int wave_s, int L) {
;     ...
;     if (L + 1 < DEPTH && bx >= 128 && bx < 224) { convert_layer(args_ptr(), L + 1, (bx - 128) * NWAVES + wave, 96 * NWAVES, lane); asm volatile("s_waitcnt vmcnt(0)" ::: "memory"); }
.Lcx5_skip:
	s_cmp_lt_u32 s2, 0xe0
	s_cbranch_scc1 .Lcx6_skip
	s_cmp_ge_u32 s2, 0xf8
	s_cbranch_scc1 .Lcx6_skip
	v_mov_b32_e32 v128, v1
	v_mov_b32_e32 v129, v2
	v_mov_b32_e32 v130, v3
	v_mov_b32_e32 v131, v64
	v_mov_b32_e32 v132, v65
	v_mov_b32_e32 v133, v66
	v_mov_b32_e32 v134, v67
	v_mov_b32_e32 v135, v68
	v_mov_b32_e32 v136, v69
	v_mov_b32_e32 v137, v70
	v_mov_b32_e32 v138, v71
	v_mov_b32_e32 v139, v72
	v_mov_b32_e32 v140, v73
	v_mov_b32_e32 v141, v74
	v_mov_b32_e32 v142, v75
	v_mov_b32_e32 v143, v76
	v_mov_b32_e32 v144, v77
	v_mov_b32_e32 v145, v78
	v_mov_b32_e32 v146, v79
	v_mov_b32_e32 v147, v81
	v_mov_b32_e32 v148, v82
	v_mov_b32_e32 v149, v83
	v_mov_b32_e32 v150, v84
	v_mov_b32_e32 v151, v85
	v_mov_b32_e32 v152, v86
	v_mov_b32_e32 v153, v87
	v_mov_b32_e32 v154, v88
	v_mov_b32_e32 v155, v89
	v_mov_b32_e32 v156, v90
	v_mov_b32_e32 v157, v91
	v_writelane_b32 v253, s1, 0
	v_writelane_b32 v253, s30, 1
	v_writelane_b32 v253, s31, 2
	v_writelane_b32 v253, s34, 3
	v_writelane_b32 v253, s35, 4
	v_writelane_b32 v253, s36, 5
	v_writelane_b32 v253, s37, 6
	v_writelane_b32 v253, s38, 7
	v_writelane_b32 v253, s39, 8
	v_writelane_b32 v253, s41, 9
	v_writelane_b32 v253, s44, 10
	v_writelane_b32 v253, s45, 11
	v_writelane_b32 v253, s46, 12
	v_writelane_b32 v253, s47, 13
	v_writelane_b32 v253, s48, 14
	v_writelane_b32 v253, s49, 15
	v_writelane_b32 v253, s50, 16
	v_writelane_b32 v253, s52, 17
	v_writelane_b32 v253, s63, 18
	v_writelane_b32 v253, s64, 19
	v_writelane_b32 v253, s65, 20
	v_writelane_b32 v253, s74, 21
	v_writelane_b32 v253, s75, 22
	v_writelane_b32 v253, s77, 23
	v_writelane_b32 v253, s82, 24
	v_writelane_b32 v253, s83, 25
	v_writelane_b32 v253, s84, 26
	v_writelane_b32 v253, s85, 27
	v_and_b32_e32 v80, 63, v201
	v_readlane_b32 s24, v252, 15
	v_readlane_b32 s25, v252, 16
	s_nop 3
	s_load_dwordx2 s[4:5], s[24:25], 0xa8
	v_readlane_b32 s1, v252, 2
	v_readlane_b32 s14, v252, 1
	s_nop 3
	s_add_i32 s1, s1, s14
	s_add_i32 s1, s1, 0x400
	v_lshlrev_b32_e32 v0, 2, v80
	s_waitcnt lgkmcnt(0)
	s_add_u32 s26, s4, 0x5400000
	s_addc_u32 s27, s5, 0
	s_add_u32 s34, s4, 0x3300000
	s_addc_u32 s35, s5, 0
	s_add_u32 s36, s4, 0x1900000
	s_addc_u32 s37, s5, 0
	s_add_u32 s38, s4, 0xb00000
	s_addc_u32 s39, s5, 0
	s_lshl_b32 s3, s1, 6
	v_and_b32_e32 v81, 0x80, v0
	v_or_b32_e32 v82, s3, v80
	s_lshl_b32 s4, s1, 5
	s_lshl_b32 s5, s1, 2
	v_mov_b32_e32 v13, 0
	s_movk_i32 s30, 0x7fff
	s_mov_b32 s31, 0xffff0000
	v_mov_b32_e32 v83, 0x2000
	v_mov_b32_e32 v84, 1
	s_mov_b32 s33, 0x1439000
	s_mov_b32 s44, 0x143c000
	s_mov_b32 s45, 0x143e000
	s_mov_b32 s46, 0x1441000
	s_mov_b32 s47, 0x1443000
	s_mov_b32 s48, 0x1446000
	s_mov_b32 s49, 0x1448000
	s_mov_b32 s50, 0x144b000
	s_mov_b32 s51, 0x144d000
	s_mov_b32 s52, 0x1450000
	s_mov_b32 s53, 0x1452000
	s_mov_b32 s54, 0x1455000
	s_mov_b32 s55, 0x1457000
	s_mov_b32 s56, 0x145a000
	s_mov_b32 s57, 0x145c000
	s_mov_b32 s58, 0x145f000
	s_mov_b32 s59, 0x1461000
	s_mov_b32 s60, 0x1464000
	s_mov_b32 s61, 0x1466000
	s_mov_b32 s62, 0x1469000
	s_mov_b32 s63, 0x146b000
	s_mov_b32 s64, 0x146e000
	s_mov_b32 s65, 0x1470000
	s_mov_b32 s66, 0x1473000
	s_mov_b32 s67, 0x1475000
	s_mov_b32 s68, 0x1478000
	s_mov_b32 s69, 0x147a000
	s_mov_b32 s70, 0x147d000
	s_mov_b32 s71, 0x147f000
	s_mov_b32 s72, 0x1482000
	s_mov_b32 s73, 0x1484000
	s_mov_b32 s74, 0x1487000
	s_mov_b32 s75, 0x1489000
	s_mov_b32 s76, 0x148c000
	s_mov_b32 s77, 0x148e000
	s_mov_b32 s78, 0x1491000
	s_mov_b32 s79, 0x1493000
	s_mov_b32 s80, 0x1496000
	s_mov_b32 s81, 0x1498000
	s_mov_b32 s82, 0x149b000
	s_mov_b32 s83, 0x149d000
	s_mov_b32 s41, 0
	s_branch .Lcx6_681

; __device__ __forceinline__ ArgsP args_ptr() { ArgsP p = (ArgsP)__builtin_amdgcn_kernarg_segment_ptr(); asm volatile("" : "+s"(p)); return p; }
; __device__ __forceinline__ void convert_layer(ArgsP a, int L, int first, int stride, int lane) {
;     unsigned char* ws = a->ws;
;     bf16* WIN = (bf16*)(ws + WS_WIN); bf16* WOUT = (bf16*)(ws + WS_WOUT); bf16* WGU = (bf16*)(ws + WS_WGU); bf16* WDN = (bf16*)(ws + WS_WDN);
;     for (int r = first; r < I_L; r += stride) {
;         if (r < I_IN) transpose_item(a->in[3] + (size_t)L * D * INW, D, INW, WIN + (size_t)L * INW * D, a->in[2] + L * D, 1, 0, r, lane);
;         else if (r < I_IN + I_OUT) transpose_item(a->in[4] + (size_t)L * D * D, D, D, WOUT + (size_t)L * D * D, nullptr, 0, 0, r - I_IN, lane);
;         else if (r < I_IN + I_OUT + I_GU) transpose_item(a->in[18] + (size_t)L * D * GU, D, GU, WGU + (size_t)L * GU * D, a->in[17] + L * D, 2, 0, r - I_IN - I_OUT, lane);
;         else transpose_item(a->in[19] + (size_t)L * FFN * D, FFN, D, WDN + (size_t)L * D * FFN, nullptr, 0, 0, r - I_IN - I_OUT - I_GU, lane);
;     }
; }
; __device__ __forceinline__ void phase_A(unsigned char* lds, int wave_s, int L) {
;     ...
;     if (L + 1 < DEPTH && bx >= 128 && bx < 224) { convert_layer(args_ptr(), L + 1, (bx - 128) * NWAVES + wave, 96 * NWAVES, lane); asm volatile("s_waitcnt vmcnt(0)" ::: "memory"); }
.LBB0_1745:
	s_or_b64 exec, exec, s[8:9]
	v_readlane_b32 s14, v252, 15
	v_readlane_b32 s15, v252, 16
	s_waitcnt lgkmcnt(0)
	v_mov_b32_e32 v0, v201
	v_readlane_b32 s0, v252, 6
	v_readlane_b32 s4, v252, 7
	s_barrier
	s_cmp_lt_u32 s2, 0x80
	s_cbranch_scc1 .Lcx8_skip
	s_cmp_ge_u32 s2, 0x100
	s_cbranch_scc1 .Lcx8_skip
	v_mov_b32_e32 v128, v0
	v_mov_b32_e32 v129, v2
	v_mov_b32_e32 v130, v3
	v_mov_b32_e32 v131, v64
	v_mov_b32_e32 v132, v65
	v_mov_b32_e32 v133, v66
	v_mov_b32_e32 v134, v67
	v_mov_b32_e32 v135, v68
	v_mov_b32_e32 v136, v69
	v_mov_b32_e32 v137, v70
	v_mov_b32_e32 v138, v71
	v_mov_b32_e32 v139, v72
	v_mov_b32_e32 v140, v73
	v_mov_b32_e32 v141, v74
	v_mov_b32_e32 v142, v75
	v_mov_b32_e32 v143, v76
	v_mov_b32_e32 v144, v77
	v_mov_b32_e32 v145, v78
	v_mov_b32_e32 v146, v79
	v_mov_b32_e32 v147, v80
	v_mov_b32_e32 v148, v81
	v_mov_b32_e32 v149, v82
	v_mov_b32_e32 v150, v83
	v_mov_b32_e32 v151, v84
	v_mov_b32_e32 v152, v85
	v_mov_b32_e32 v153, v86
	v_mov_b32_e32 v154, v87
	v_mov_b32_e32 v155, v88
	v_mov_b32_e32 v156, v89
	v_mov_b32_e32 v157, v90
	v_mov_b32_e32 v158, v91
	v_writelane_b32 v253, s0, 0
	v_writelane_b32 v253, s4, 1
	v_writelane_b32 v253, s14, 2
	v_writelane_b32 v253, s15, 3
	v_writelane_b32 v253, s44, 4
	v_writelane_b32 v253, s45, 5
	v_and_b32_e32 v80, 63, v201
	v_readlane_b32 s14, v252, 15
	v_readlane_b32 s15, v252, 16
	s_load_dwordx2 s[12:13], s[14:15], 0xa8
	v_readlane_b32 s0, v252, 1
	v_readlane_b32 s3, v252, 2
	s_add_i32 s0, s3, s0
	s_add_i32 s3, s0, 0x300
	s_waitcnt lgkmcnt(0)
	s_add_u32 s20, s12, 0x5980000
	s_addc_u32 s21, s13, 0
	s_add_u32 s22, s12, 0x3e00000
	s_addc_u32 s23, s13, 0
	s_add_u32 s42, s12, 0x1b00000
	s_addc_u32 s43, s13, 0
	s_add_u32 s44, s12, 0x1000000
	v_lshlrev_b32_e32 v0, 2, v80
	s_addc_u32 s45, s13, 0
	s_lshl_b32 s12, s3, 6
	v_and_b32_e32 v81, 0x80, v0
	v_or_b32_e32 v82, s12, v80
	s_lshl_b32 s13, s3, 5
	s_lshl_b32 s40, s3, 2
	v_mov_b32_e32 v13, 0
	s_movk_i32 s48, 0x7fff
	s_mov_b32 s49, 0xffff0000
	v_mov_b32_e32 v83, 0x3000
	v_mov_b32_e32 v84, 1
	s_mov_b32 s50, 0x1e9b000
	s_mov_b32 s51, 0x1e9d000
	s_mov_b32 s47, 0
	s_branch .Lcx8_1157

; __device__ __forceinline__ ArgsP args_ptr() { ArgsP p = (ArgsP)__builtin_amdgcn_kernarg_segment_ptr(); asm volatile("" : "+s"(p)); return p; }
; __device__ __forceinline__ void convert_layer(ArgsP a, int L, int first, int stride, int lane) {
;     unsigned char* ws = a->ws;
;     bf16* WIN = (bf16*)(ws + WS_WIN); bf16* WOUT = (bf16*)(ws + WS_WOUT); bf16* WGU = (bf16*)(ws + WS_WGU); bf16* WDN = (bf16*)(ws + WS_WDN);
;     for (int r = first; r < I_L; r += stride) {
;         if (r < I_IN) transpose_item(a->in[3] + (size_t)L * D * INW, D, INW, WIN + (size_t)L * INW * D, a->in[2] + L * D, 1, 0, r, lane);
;         else if (r < I_IN + I_OUT) transpose_item(a->in[4] + (size_t)L * D * D, D, D, WOUT + (size_t)L * D * D, nullptr, 0, 0, r - I_IN, lane);
;         else if (r < I_IN + I_OUT + I_GU) transpose_item(a->in[18] + (size_t)L * D * GU, D, GU, WGU + (size_t)L * GU * D, a->in[17] + L * D, 2, 0, r - I_IN - I_OUT, lane);
;         else transpose_item(a->in[19] + (size_t)L * FFN * D, FFN, D, WDN + (size_t)L * D * FFN, nullptr, 0, 0, r - I_IN - I_OUT - I_GU, lane);
;     }
; }
; __device__ __forceinline__ void phase_A(unsigned char* lds, int wave_s, int L) {
;     ...
;     if (L + 1 < DEPTH && bx >= 128 && bx < 224) { convert_layer(args_ptr(), L + 1, (bx - 128) * NWAVES + wave, 96 * NWAVES, lane); asm volatile("s_waitcnt vmcnt(0)" ::: "memory"); }
.Lcx8_skip:
	s_cmp_lt_u32 s2, 0xe0
	s_cbranch_scc1 .Lcx9_skip
	s_cmp_ge_u32 s2, 0xf8
	s_cbranch_scc1 .Lcx9_skip
	v_mov_b32_e32 v128, v0
	v_mov_b32_e32 v129, v2
	v_mov_b32_e32 v130, v3
	v_mov_b32_e32 v131, v64
	v_mov_b32_e32 v132, v65
	v_mov_b32_e32 v133, v66
	v_mov_b32_e32 v134, v67
	v_mov_b32_e32 v135, v68
	v_mov_b32_e32 v136, v69
	v_mov_b32_e32 v137, v70
	v_mov_b32_e32 v138, v71
	v_mov_b32_e32 v139, v72
	v_mov_b32_e32 v140, v73
	v_mov_b32_e32 v141, v74
	v_mov_b32_e32 v142, v75
	v_mov_b32_e32 v143, v76
	v_mov_b32_e32 v144, v77
	v_mov_b32_e32 v145, v78
	v_mov_b32_e32 v146, v79
	v_mov_b32_e32 v147, v80
	v_mov_b32_e32 v148, v81
	v_mov_b32_e32 v149, v82
	v_mov_b32_e32 v150, v83
	v_mov_b32_e32 v151, v84
	v_mov_b32_e32 v152, v85
	v_mov_b32_e32 v153, v86
	v_mov_b32_e32 v154, v87
	v_mov_b32_e32 v155, v88
	v_mov_b32_e32 v156, v89
	v_mov_b32_e32 v157, v90
	v_mov_b32_e32 v158, v91
	v_writelane_b32 v253, s0, 0
	v_writelane_b32 v253, s4, 1
	v_writelane_b32 v253, s14, 2
	v_writelane_b32 v253, s15, 3
	v_writelane_b32 v253, s44, 4
	v_writelane_b32 v253, s45, 5
	v_and_b32_e32 v80, 63, v201
	v_readlane_b32 s14, v252, 15
	v_readlane_b32 s15, v252, 16
	s_load_dwordx2 s[12:13], s[14:15], 0xa8
	v_readlane_b32 s0, v252, 1
	v_readlane_b32 s3, v252, 2
	s_add_i32 s0, s3, s0
	s_add_i32 s3, s0, 0x400
	s_waitcnt lgkmcnt(0)
	s_add_u32 s20, s12, 0x5980000
	s_addc_u32 s21, s13, 0
	s_add_u32 s22, s12, 0x3e00000
	s_addc_u32 s23, s13, 0
	s_add_u32 s42, s12, 0x1b00000
	s_addc_u32 s43, s13, 0
	s_add_u32 s44, s12, 0x1000000
	v_lshlrev_b32_e32 v0, 2, v80
	s_addc_u32 s45, s13, 0
	s_lshl_b32 s12, s3, 6
	v_and_b32_e32 v81, 0x80, v0
	v_or_b32_e32 v82, s12, v80
	s_lshl_b32 s13, s3, 5
	s_lshl_b32 s40, s3, 2
	v_mov_b32_e32 v13, 0
	s_movk_i32 s48, 0x7fff
	s_mov_b32 s49, 0xffff0000
	v_mov_b32_e32 v83, 0x3000
	v_mov_b32_e32 v84, 1
	s_mov_b32 s50, 0x1e9b000
	s_mov_b32 s51, 0x1e9d000
	s_mov_b32 s47, 0
	s_branch .Lcx9_1157
